# v37 plus NA: next group's K-fragment ds_reads issued before the current group's QK MFMAs (renamed fragment registers, counted lgkmcnt)
# baseline (speedup 1.0000x reference)
; #define LAS __attribute__((address_space(3)))
; #define MFMA32(a, b, c) __builtin_amdgcn_mfma_f32_16x16x32_bf16((a), (b), (c), 0, 0, 0)
; DI void na_phase(LAS unsigned char* lds, const Args& A, const bf16* proj, bf16* nao, int T, int nB, unsigned* counter, int tid_in) {
;     ...
;             for (int rr = 0; rr < 4; ++rr) { const int kr = rs + 4 * kh + rr, sl = kr & 7;
; #pragma unroll
;                 for (int ct = 0; ct < 2; ++ct) { const int cm = cs0 + 16 * ct + l15; f32x4 acc = (f32x4){0.f, 0.f, 0.f, 0.f};
; #pragma unroll
;                     for (int ks = 0; ks < 2; ++ks) { const bf16x8 kf = *(const LAS bf16x8*)(lds + NA_K + sl * 8192 + cm * 128 + (((4 * ks + g) ^ ((cm >> 1) & 7)) * 16)); acc = MFMA32(kf, qf[ks], acc); }
; #pragma unroll
;                     for (int e = 0; e < 4; ++e) { const int cc = cs0 + 16 * ct + 4 * g + e; const bool valid = (cc >= csq) && (cc < csq + 16);
;                         const int bi = (kr - r + 7) * 31 + min(max(cc - cq + 15, 0), 30);
;                         const float sv = valid ? acc[e] + BI[bi] : -INFINITY; acc[e] = sv; mx = fmaxf(mx, sv); }
.LBB0_337:
	v_add_u32_e32 v31, s38, v71
	v_lshlrev_b32_e32 v24, 13, v31
	v_and_b32_e32 v28, 0xe000, v24
	v_add_u32_e32 v30, 0, v28
	v_add_u32_e32 v29, v30, v91
	v_add_u32_e32 v24, v29, v92
	ds_read_b128 v[24:27], v24
	v_add_u32_e32 v29, v29, v93
	ds_read_b128 v[58:61], v29
	s_add_i32 s0, s19, s38
	v_add_u32_e32 v29, s0, v57
	v_mul_lo_u32 v29, v29, s88
	v_add_u32_e32 v38, s87, v29
	v_add_u32_e32 v29, 0xfffff080, v38
	v_mov_b32_e32 v63, 0xff800000
	v_lshl_add_u32 v252, v94, 2, v29
	ds_read_b32 v252, v252 offset:868
	v_lshl_add_u32 v253, v95, 2, v29
	ds_read_b32 v253, v253 offset:868
	v_lshl_add_u32 v254, v96, 2, v29
	ds_read_b32 v254, v254 offset:868
	v_lshl_add_u32 v255, v97, 2, v29
	ds_read_b32 v255, v255 offset:868
	v_add_u32_e32 v30, v30, v98
	v_add_u32_e32 v156, v30, v92
	ds_read_b128 v[140:143], v156
	v_add_u32_e32 v30, v30, v93
	ds_read_b128 v[144:147], v30
	s_waitcnt lgkmcnt(7)
	v_mfma_f32_16x16x32_bf16 v[24:27], v[24:27], v[20:23], 0
	s_waitcnt lgkmcnt(6)
	v_mfma_f32_16x16x32_bf16 v[24:27], v[58:61], v[16:19], v[24:27]
	v_mov_b32_e32 v59, 0xff800000
	s_waitcnt lgkmcnt(2)
	s_nop 5
	s_and_saveexec_b64 s[0:1], s[14:15]
	v_add_f32_e32 v63, v24, v252
	s_or_b64 exec, exec, s[0:1]
	s_and_saveexec_b64 s[0:1], s[16:17]
	v_add_f32_e32 v59, v25, v253
	s_or_b64 exec, exec, s[0:1]
	v_mov_b32_e32 v56, 0xff800000
	v_mov_b32_e32 v62, 0xff800000
	s_and_saveexec_b64 s[0:1], s[48:49]
	v_add_f32_e32 v62, v26, v254
	s_or_b64 exec, exec, s[0:1]
	s_and_saveexec_b64 s[0:1], s[50:51]
	v_add_f32_e32 v56, v27, v255
	s_or_b64 exec, exec, s[0:1]
	v_mov_b32_e32 v39, 0xff800000
	v_lshl_add_u32 v252, v99, 2, v29
	ds_read_b32 v252, v252 offset:868
	v_lshl_add_u32 v253, v100, 2, v29
	ds_read_b32 v253, v253 offset:868
	v_lshl_add_u32 v254, v101, 2, v29
	ds_read_b32 v254, v254 offset:868
	v_lshl_add_u32 v255, v102, 2, v29
	ds_read_b32 v255, v255 offset:868
	v_lshl_add_u32 v156, v31, 13, v212
	v_and_b32_e32 v29, 0xe000, v156
	v_add_u32_e32 v66, 0, v29
	v_add_u32_e32 v30, v66, v91
	v_add_u32_e32 v156, v30, v92
	ds_read_b128 v[148:151], v156
	v_add_u32_e32 v30, v30, v93
	ds_read_b128 v[152:155], v30
	s_waitcnt lgkmcnt(7)
	v_mfma_f32_16x16x32_bf16 v[24:27], v[140:143], v[20:23], 0
	s_waitcnt lgkmcnt(6)
	v_mfma_f32_16x16x32_bf16 v[24:27], v[144:147], v[16:19], v[24:27]
	v_mov_b32_e32 v65, 0xff800000
	s_waitcnt lgkmcnt(2)
	s_nop 5
	s_and_saveexec_b64 s[0:1], s[52:53]
	v_add_f32_e32 v65, v24, v252
	s_or_b64 exec, exec, s[0:1]
	s_and_saveexec_b64 s[0:1], s[56:57]
	v_add_f32_e32 v39, v25, v253
	s_or_b64 exec, exec, s[0:1]
	v_mov_b32_e32 v54, 0xff800000
	v_mov_b32_e32 v55, 0xff800000
	s_and_saveexec_b64 s[0:1], s[76:77]
	v_add_f32_e32 v55, v26, v254
	s_or_b64 exec, exec, s[0:1]
	s_and_saveexec_b64 s[0:1], s[66:67]
	v_add_f32_e32 v54, v27, v255
	s_or_b64 exec, exec, s[0:1]
	v_add_u32_e32 v30, 0xfffff0fc, v38
	v_mov_b32_e32 v58, 0xff800000
	v_mov_b32_e32 v60, 0xff800000
	v_lshl_add_u32 v252, v94, 2, v30
	ds_read_b32 v252, v252 offset:868
	v_lshl_add_u32 v253, v95, 2, v30
	ds_read_b32 v253, v253 offset:868
	v_lshl_add_u32 v254, v96, 2, v30
	ds_read_b32 v254, v254 offset:868
	v_lshl_add_u32 v255, v97, 2, v30
	ds_read_b32 v255, v255 offset:868
	v_add_u32_e32 v66, v66, v98
	v_add_u32_e32 v156, v66, v92
	ds_read_b128 v[140:143], v156
	v_add_u32_e32 v66, v66, v93
	ds_read_b128 v[144:147], v66
	s_waitcnt lgkmcnt(7)
	v_mfma_f32_16x16x32_bf16 v[24:27], v[148:151], v[20:23], 0
	s_waitcnt lgkmcnt(6)
	v_mfma_f32_16x16x32_bf16 v[24:27], v[152:155], v[16:19], v[24:27]
	s_waitcnt lgkmcnt(2)
	s_nop 5
	s_and_saveexec_b64 s[0:1], s[14:15]
	v_add_f32_e32 v60, v24, v252
	s_or_b64 exec, exec, s[0:1]
	s_and_saveexec_b64 s[0:1], s[16:17]
	v_add_f32_e32 v58, v25, v253
	s_or_b64 exec, exec, s[0:1]
	v_mov_b32_e32 v61, 0xff800000
	v_mov_b32_e32 v64, 0xff800000
	s_and_saveexec_b64 s[0:1], s[48:49]
	v_add_f32_e32 v64, v26, v254
	s_or_b64 exec, exec, s[0:1]
	s_and_saveexec_b64 s[0:1], s[50:51]
	v_add_f32_e32 v61, v27, v255
	s_or_b64 exec, exec, s[0:1]
	v_mov_b32_e32 v66, 0xff800000
	v_mov_b32_e32 v67, 0xff800000
	v_lshl_add_u32 v252, v99, 2, v30
	ds_read_b32 v252, v252 offset:868
	v_lshl_add_u32 v253, v100, 2, v30
	ds_read_b32 v253, v253 offset:868
	v_lshl_add_u32 v254, v101, 2, v30
	ds_read_b32 v254, v254 offset:868
	v_lshl_add_u32 v255, v102, 2, v30
	ds_read_b32 v255, v255 offset:868
	v_lshl_add_u32 v156, v31, 13, v213
	v_and_b32_e32 v30, 0xe000, v156
	v_add_u32_e32 v110, 0, v30
	v_add_u32_e32 v106, v110, v91
	v_add_u32_e32 v156, v106, v92
	ds_read_b128 v[148:151], v156
	v_add_u32_e32 v106, v106, v93
	ds_read_b128 v[152:155], v106
	s_waitcnt lgkmcnt(7)
	v_mfma_f32_16x16x32_bf16 v[24:27], v[140:143], v[20:23], 0
	s_waitcnt lgkmcnt(6)
	v_mfma_f32_16x16x32_bf16 v[24:27], v[144:147], v[16:19], v[24:27]
	s_waitcnt lgkmcnt(2)
	s_nop 5
	s_and_saveexec_b64 s[0:1], s[52:53]
	v_add_f32_e32 v67, v24, v252
	s_or_b64 exec, exec, s[0:1]
	s_and_saveexec_b64 s[0:1], s[56:57]
	v_add_f32_e32 v66, v25, v253
	s_or_b64 exec, exec, s[0:1]
	v_mov_b32_e32 v104, 0xff800000
	v_mov_b32_e32 v105, 0xff800000
	s_and_saveexec_b64 s[0:1], s[76:77]
	v_add_f32_e32 v105, v26, v254
	s_or_b64 exec, exec, s[0:1]
	s_and_saveexec_b64 s[0:1], s[66:67]
	v_add_f32_e32 v104, v27, v255
	s_or_b64 exec, exec, s[0:1]
	v_add_u32_e32 v114, 0xfffff178, v38
	v_lshl_add_u32 v252, v94, 2, v114
	ds_read_b32 v252, v252 offset:868
	v_lshl_add_u32 v253, v95, 2, v114
	ds_read_b32 v253, v253 offset:868
	v_lshl_add_u32 v254, v96, 2, v114
	ds_read_b32 v254, v254 offset:868
	v_lshl_add_u32 v255, v97, 2, v114
	ds_read_b32 v255, v255 offset:868
	v_add_u32_e32 v110, v110, v98
	v_add_u32_e32 v156, v110, v92
	ds_read_b128 v[140:143], v156
	v_add_u32_e32 v110, v110, v93
	ds_read_b128 v[144:147], v110
	s_waitcnt lgkmcnt(7)
; #define LAS __attribute__((address_space(3)))
; #define MFMA32(a, b, c) __builtin_amdgcn_mfma_f32_16x16x32_bf16((a), (b), (c), 0, 0, 0)
; DI void na_phase(LAS unsigned char* lds, const Args& A, const bf16* proj, bf16* nao, int T, int nB, unsigned* counter, int tid_in) {
;     ...
;             for (int rr = 0; rr < 4; ++rr) { const int kr = rs + 4 * kh + rr, sl = kr & 7;
; #pragma unroll
;                 for (int ct = 0; ct < 2; ++ct) { const int cm = cs0 + 16 * ct + l15; f32x4 acc = (f32x4){0.f, 0.f, 0.f, 0.f};
; #pragma unroll
;                     for (int ks = 0; ks < 2; ++ks) { const bf16x8 kf = *(const LAS bf16x8*)(lds + NA_K + sl * 8192 + cm * 128 + (((4 * ks + g) ^ ((cm >> 1) & 7)) * 16)); acc = MFMA32(kf, qf[ks], acc); }
; #pragma unroll
;                     for (int e = 0; e < 4; ++e) { const int cc = cs0 + 16 * ct + 4 * g + e; const bool valid = (cc >= csq) && (cc < csq + 16);
;                         const int bi = (kr - r + 7) * 31 + min(max(cc - cq + 15, 0), 30);
;                         const float sv = valid ? acc[e] + BI[bi] : -INFINITY; acc[e] = sv; mx = fmaxf(mx, sv); }
;                     sT[rr][ct] = acc; } }
;             mx = fmaxf(mx, __shfl_xor(mx, 16)); mx = fmaxf(mx, __shfl_xor(mx, 32));
	v_mfma_f32_16x16x32_bf16 v[24:27], v[148:151], v[20:23], 0
	s_waitcnt lgkmcnt(6)
	v_mfma_f32_16x16x32_bf16 v[24:27], v[152:155], v[16:19], v[24:27]
	v_mov_b32_e32 v106, 0xff800000
	v_mov_b32_e32 v107, 0xff800000
	s_waitcnt lgkmcnt(2)
	s_nop 5
	s_and_saveexec_b64 s[0:1], s[14:15]
	v_add_f32_e32 v107, v24, v252
	s_or_b64 exec, exec, s[0:1]
	s_and_saveexec_b64 s[0:1], s[16:17]
	v_add_f32_e32 v106, v25, v253
	s_or_b64 exec, exec, s[0:1]
	v_mov_b32_e32 v108, 0xff800000
	v_mov_b32_e32 v109, 0xff800000
	s_and_saveexec_b64 s[0:1], s[48:49]
	v_add_f32_e32 v109, v26, v254
	s_or_b64 exec, exec, s[0:1]
	s_and_saveexec_b64 s[0:1], s[50:51]
	v_add_f32_e32 v108, v27, v255
	s_or_b64 exec, exec, s[0:1]
	v_lshl_add_u32 v252, v99, 2, v114
	ds_read_b32 v252, v252 offset:868
	v_lshl_add_u32 v253, v100, 2, v114
	ds_read_b32 v253, v253 offset:868
	v_lshl_add_u32 v254, v101, 2, v114
	ds_read_b32 v254, v254 offset:868
	v_lshl_add_u32 v255, v102, 2, v114
	ds_read_b32 v255, v255 offset:868
	v_lshl_add_u32 v156, v31, 13, v214
	v_and_b32_e32 v31, 0xe000, v156
	v_add_u32_e32 v116, 0, v31
	v_add_u32_e32 v114, v116, v91
	v_add_u32_e32 v156, v114, v92
	ds_read_b128 v[148:151], v156
	v_add_u32_e32 v114, v114, v93
	ds_read_b128 v[152:155], v114
	s_waitcnt lgkmcnt(7)
	v_mfma_f32_16x16x32_bf16 v[24:27], v[140:143], v[20:23], 0
	s_waitcnt lgkmcnt(6)
	v_mfma_f32_16x16x32_bf16 v[24:27], v[144:147], v[16:19], v[24:27]
	v_mov_b32_e32 v110, 0xff800000
	v_mov_b32_e32 v111, 0xff800000
	s_waitcnt lgkmcnt(2)
	s_nop 5
	s_and_saveexec_b64 s[0:1], s[52:53]
	v_add_f32_e32 v111, v24, v252
	s_or_b64 exec, exec, s[0:1]
	s_and_saveexec_b64 s[0:1], s[56:57]
	v_add_f32_e32 v110, v25, v253
	s_or_b64 exec, exec, s[0:1]
	v_mov_b32_e32 v112, 0xff800000
	v_mov_b32_e32 v113, 0xff800000
	s_and_saveexec_b64 s[0:1], s[76:77]
	v_add_f32_e32 v113, v26, v254
	s_or_b64 exec, exec, s[0:1]
	s_and_saveexec_b64 s[0:1], s[66:67]
	v_add_f32_e32 v112, v27, v255
	s_or_b64 exec, exec, s[0:1]
	v_add_u32_e32 v38, 0xfffff1f4, v38
	v_mov_b32_e32 v114, 0xff800000
	v_mov_b32_e32 v115, 0xff800000
	v_lshl_add_u32 v252, v94, 2, v38
	ds_read_b32 v252, v252 offset:868
	v_lshl_add_u32 v253, v95, 2, v38
	ds_read_b32 v253, v253 offset:868
	s_waitcnt lgkmcnt(3)
	v_mfma_f32_16x16x32_bf16 v[24:27], v[148:151], v[20:23], 0
	s_waitcnt lgkmcnt(2)
	v_mfma_f32_16x16x32_bf16 v[24:27], v[152:155], v[16:19], v[24:27]
	s_waitcnt lgkmcnt(0)
	s_nop 5
	s_and_saveexec_b64 s[0:1], s[14:15]
	v_add_f32_e32 v115, v24, v252
	s_or_b64 exec, exec, s[0:1]
	s_and_saveexec_b64 s[0:1], s[16:17]
	v_add_f32_e32 v114, v25, v253
	s_or_b64 exec, exec, s[0:1]
	s_nop 1
	v_mov_b32_e32 v24, 0xff800000
	v_mov_b32_e32 v25, 0xff800000
	v_lshl_add_u32 v252, v96, 2, v38
	ds_read_b32 v252, v252 offset:868
	v_lshl_add_u32 v253, v97, 2, v38
	ds_read_b32 v253, v253 offset:868
	s_waitcnt lgkmcnt(0)
	s_nop 2
	s_and_saveexec_b64 s[0:1], s[48:49]
	v_add_f32_e32 v25, v26, v252
	s_or_b64 exec, exec, s[0:1]
	s_and_saveexec_b64 s[0:1], s[50:51]
	v_add_f32_e32 v24, v27, v253
	s_or_b64 exec, exec, s[0:1]
	v_add_u32_e32 v26, v116, v98
	v_add_u32_e32 v27, v26, v92
	ds_read_b128 v[116:119], v27
	v_add_u32_e32 v26, v26, v93
	s_waitcnt lgkmcnt(0)
	v_mfma_f32_16x16x32_bf16 v[20:23], v[116:119], v[20:23], 0
	ds_read_b128 v[116:119], v26
	s_waitcnt lgkmcnt(0)
	v_mfma_f32_16x16x32_bf16 v[16:19], v[116:119], v[16:19], v[20:23]
	s_nop 4
	v_mov_b32_e32 v20, 0xff800000
	v_mov_b32_e32 v21, 0xff800000
	v_lshl_add_u32 v252, v99, 2, v38
	ds_read_b32 v252, v252 offset:868
	v_lshl_add_u32 v253, v100, 2, v38
	ds_read_b32 v253, v253 offset:868
	v_lshl_add_u32 v254, v101, 2, v38
	ds_read_b32 v254, v254 offset:868
	v_lshl_add_u32 v255, v102, 2, v38
	ds_read_b32 v255, v255 offset:868
	s_waitcnt lgkmcnt(0)
	s_and_saveexec_b64 s[0:1], s[52:53]
	v_add_f32_e32 v21, v16, v252
	s_or_b64 exec, exec, s[0:1]
	s_and_saveexec_b64 s[0:1], s[56:57]
	v_add_f32_e32 v20, v17, v253
	s_or_b64 exec, exec, s[0:1]
	v_mov_b32_e32 v16, 0xff800000
	v_mov_b32_e32 v17, 0xff800000
	s_and_saveexec_b64 s[0:1], s[76:77]
	v_add_f32_e32 v17, v18, v254
	s_or_b64 exec, exec, s[0:1]
	s_and_saveexec_b64 s[0:1], s[66:67]
	v_add_f32_e32 v16, v19, v255
	s_or_b64 exec, exec, s[0:1]
	v_max3_f32 v18, v63, s89, v59
	v_max3_f32 v18, v18, v62, v56
	v_max3_f32 v18, v18, v65, v39
	v_max3_f32 v18, v18, v55, v54
	v_max3_f32 v18, v18, v60, v58
	v_max3_f32 v18, v18, v64, v61
	v_max3_f32 v18, v18, v67, v66
	v_max3_f32 v18, v18, v105, v104
	v_max3_f32 v18, v18, v107, v106
	v_max3_f32 v18, v18, v109, v108
	v_max3_f32 v18, v18, v111, v110
	v_max3_f32 v18, v18, v113, v112
	v_max3_f32 v18, v18, v115, v114
	v_max3_f32 v18, v18, v25, v24
	v_max3_f32 v18, v18, v21, v20
	v_max3_f32 v18, v18, v17, v16
	ds_bpermute_b32 v19, v72, v18
	s_waitcnt lgkmcnt(0)
	v_max_f32_e32 v19, v19, v19
	v_max_f32_e32 v18, v18, v19
	ds_bpermute_b32 v19, v73, v18
	s_waitcnt lgkmcnt(0)
; #define LAS __attribute__((address_space(3)))
; DI unsigned pk2(float lo, float hi) { f32x2 v = {lo, hi}; bf16v2 b = __builtin_convertvector(v, bf16v2); return __builtin_bit_cast(unsigned, b); }
; #define MFMA32(a, b, c) __builtin_amdgcn_mfma_f32_16x16x32_bf16((a), (b), (c), 0, 0, 0)
; DI void na_phase(LAS unsigned char* lds, const Args& A, const bf16* proj, bf16* nao, int T, int nB, unsigned* counter, int tid_in) {
;     ...
;             mx = fmaxf(mx, __shfl_xor(mx, 16)); mx = fmaxf(mx, __shfl_xor(mx, 32));
;             float lsum = 0.f;
; #pragma unroll
;             for (int rr = 0; rr < 4; ++rr)
; #pragma unroll
;                 for (int ct = 0; ct < 2; ++ct)
; #pragma unroll
;                     for (int e = 0; e < 4; ++e) { const float p = __expf(sT[rr][ct][e] - mx); sT[rr][ct][e] = p; lsum += p; }
;             lsum += __shfl_xor(lsum, 16); lsum += __shfl_xor(lsum, 32);
;             f32x4 O[4];
; #pragma unroll
;             for (int mt = 0; mt < 4; ++mt) O[mt] = (f32x4){0.f, 0.f, 0.f, 0.f};
; #pragma unroll
;             for (int rr = 0; rr < 4; ++rr) { const int sl = (rs + 4 * kh + rr) & 7;
;                 const u32x4 pw = (u32x4){pk2(sT[rr][0][0], sT[rr][0][1]), pk2(sT[rr][0][2], sT[rr][0][3]), pk2(sT[rr][1][0], sT[rr][1][1]), pk2(sT[rr][1][2], sT[rr][1][3])};
;                 const bf16x8 pb = __builtin_bit_cast(bf16x8, pw);
; #pragma unroll
;                 for (int mt = 0; mt < 4; ++mt) { const int dd = 16 * mt + l15, sw = 2 * ((dd >> 1) & 7);
;                     const LAS unsigned char* vb = lds + NA_V + sl * 8192 + dd * 128;
;                     const u32x2 lo = *(const LAS u32x2*)(vb + ((((cs0 >> 2) + g) ^ sw) * 8)), hi = *(const LAS u32x2*)(vb + ((((cs0 >> 2) + 4 + g) ^ sw) * 8));
;                     const u32x4 vv = (u32x4){lo.x, lo.y, hi.x, hi.y};
;                     O[mt] = MFMA32(__builtin_bit_cast(bf16x8, vv), pb, O[mt]); } }
	v_max_f32_e32 v19, v19, v19
	v_max_f32_e32 v38, v18, v19
	v_sub_f32_e32 v39, v39, v38
	v_mul_f32_e32 v39, 0x3fb8aa3b, v39
	v_sub_f32_e32 v26, v56, v38
	v_exp_f32_e32 v56, v39
	v_sub_f32_e32 v39, v55, v38
	v_mul_f32_e32 v39, 0x3fb8aa3b, v39
	v_exp_f32_e32 v55, v39
	v_sub_f32_e32 v39, v54, v38
	v_mul_f32_e32 v39, 0x3fb8aa3b, v39
	v_sub_f32_e32 v22, v59, v38
	v_exp_f32_e32 v59, v39
	v_sub_f32_e32 v39, v60, v38
	v_mul_f32_e32 v39, 0x3fb8aa3b, v39
	v_exp_f32_e32 v116, v39
	v_sub_f32_e32 v39, v58, v38
	v_mul_f32_e32 v39, 0x3fb8aa3b, v39
	v_exp_f32_e32 v117, v39
	v_sub_f32_e32 v39, v64, v38
	v_mul_f32_e32 v39, 0x3fb8aa3b, v39
	v_exp_f32_e32 v118, v39
	v_sub_f32_e32 v39, v61, v38
	v_mul_f32_e32 v39, 0x3fb8aa3b, v39
	v_exp_f32_e32 v119, v39
	v_sub_f32_e32 v39, v67, v38
	v_sub_f32_e32 v18, v63, v38
	v_mul_f32_e32 v39, 0x3fb8aa3b, v39
	v_mul_f32_e32 v18, 0x3fb8aa3b, v18
	v_exp_f32_e32 v67, v39
	v_sub_f32_e32 v39, v66, v38
	v_exp_f32_e32 v18, v18
	v_mul_f32_e32 v22, 0x3fb8aa3b, v22
	v_sub_f32_e32 v23, v62, v38
	v_mul_f32_e32 v39, 0x3fb8aa3b, v39
	v_exp_f32_e32 v22, v22
	v_mul_f32_e32 v23, 0x3fb8aa3b, v23
	v_exp_f32_e32 v66, v39
	v_sub_f32_e32 v39, v105, v38
	v_exp_f32_e32 v23, v23
	v_mul_f32_e32 v26, 0x3fb8aa3b, v26
	v_sub_f32_e32 v27, v65, v38
	v_mul_f32_e32 v39, 0x3fb8aa3b, v39
	v_exp_f32_e32 v26, v26
	v_mul_f32_e32 v27, 0x3fb8aa3b, v27
	v_exp_f32_e32 v120, v39
	v_sub_f32_e32 v39, v104, v38
	v_add_f32_e32 v19, 0, v18
	v_exp_f32_e32 v27, v27
	v_mul_f32_e32 v39, 0x3fb8aa3b, v39
	v_add_f32_e32 v19, v22, v19
	v_exp_f32_e32 v121, v39
	v_sub_f32_e32 v39, v107, v38
	v_add_f32_e32 v19, v23, v19
	v_mul_f32_e32 v39, 0x3fb8aa3b, v39
	v_add_f32_e32 v19, v26, v19
	v_exp_f32_e32 v122, v39
	v_sub_f32_e32 v39, v106, v38
	v_add_f32_e32 v19, v27, v19
	v_mul_f32_e32 v39, 0x3fb8aa3b, v39
	v_add_f32_e32 v19, v56, v19
	v_exp_f32_e32 v123, v39
	v_sub_f32_e32 v39, v109, v38
	v_add_f32_e32 v19, v55, v19
	v_mul_f32_e32 v39, 0x3fb8aa3b, v39
	v_add_f32_e32 v19, v59, v19
	v_exp_f32_e32 v124, v39
	v_sub_f32_e32 v39, v108, v38
	v_add_f32_e32 v19, v116, v19
	v_mul_f32_e32 v39, 0x3fb8aa3b, v39
	v_add_f32_e32 v19, v117, v19
	v_exp_f32_e32 v125, v39
	v_sub_f32_e32 v39, v111, v38
	v_add_f32_e32 v19, v118, v19
	v_mul_f32_e32 v39, 0x3fb8aa3b, v39
	v_add_f32_e32 v19, v119, v19
	v_exp_f32_e32 v126, v39
	v_sub_f32_e32 v39, v110, v38
	v_add_f32_e32 v19, v67, v19
	v_mul_f32_e32 v39, 0x3fb8aa3b, v39
	v_add_f32_e32 v19, v66, v19
	v_exp_f32_e32 v127, v39
	v_sub_f32_e32 v39, v113, v38
	v_add_f32_e32 v19, v120, v19
	v_mul_f32_e32 v39, 0x3fb8aa3b, v39
	v_add_f32_e32 v19, v121, v19
	v_exp_f32_e32 v128, v39
	v_sub_f32_e32 v39, v112, v38
	v_add_f32_e32 v19, v122, v19
	v_mul_f32_e32 v39, 0x3fb8aa3b, v39
	v_add_f32_e32 v19, v123, v19
	v_exp_f32_e32 v129, v39
	v_sub_f32_e32 v39, v115, v38
	v_add_f32_e32 v19, v124, v19
	v_mul_f32_e32 v39, 0x3fb8aa3b, v39
	v_add_f32_e32 v19, v125, v19
	v_exp_f32_e32 v130, v39
	v_sub_f32_e32 v39, v114, v38
	v_add_f32_e32 v19, v126, v19
	v_mul_f32_e32 v39, 0x3fb8aa3b, v39
	v_sub_f32_e32 v25, v25, v38
	v_add_f32_e32 v19, v127, v19
	v_exp_f32_e32 v131, v39
	v_mul_f32_e32 v25, 0x3fb8aa3b, v25
	v_sub_f32_e32 v24, v24, v38
	v_add_f32_e32 v19, v128, v19
	v_exp_f32_e32 v132, v25
	v_mul_f32_e32 v24, 0x3fb8aa3b, v24
	v_sub_f32_e32 v21, v21, v38
	v_add_f32_e32 v19, v129, v19
	v_exp_f32_e32 v133, v24
	v_mul_f32_e32 v21, 0x3fb8aa3b, v21
	v_sub_f32_e32 v20, v20, v38
	v_add_f32_e32 v19, v130, v19
	v_exp_f32_e32 v134, v21
	v_mul_f32_e32 v20, 0x3fb8aa3b, v20
	v_sub_f32_e32 v17, v17, v38
	v_add_f32_e32 v19, v131, v19
	v_exp_f32_e32 v135, v20
	v_mul_f32_e32 v17, 0x3fb8aa3b, v17
	v_sub_f32_e32 v16, v16, v38
	v_add_f32_e32 v19, v132, v19
	v_exp_f32_e32 v136, v17
	v_mul_f32_e32 v16, 0x3fb8aa3b, v16
	v_add_f32_e32 v19, v133, v19
	v_exp_f32_e32 v137, v16
	v_add_f32_e32 v19, v134, v19
	v_add_f32_e32 v19, v135, v19
	v_add_f32_e32 v17, v136, v19
	v_add_f32_e32 v16, v137, v17
	ds_bpermute_b32 v17, v72, v16
	v_add_u32_e32 v24, v74, v28
	v_cvt_pk_bf16_f32 v19, v55, v59
	v_add_u32_e32 v28, v24, v75
	v_add_u32_e32 v55, v24, v76
	s_waitcnt lgkmcnt(0)
	v_add_f32_e32 v39, v16, v17
	v_cvt_pk_bf16_f32 v16, v18, v22
	v_cvt_pk_bf16_f32 v17, v23, v26
	v_cvt_pk_bf16_f32 v18, v27, v56
	ds_read2st64_b64 v[20:23], v28 offset1:4
	ds_read2st64_b64 v[24:27], v55 offset1:4
	ds_bpermute_b32 v54, v73, v39
	s_waitcnt lgkmcnt(2)
	v_mov_b32_e32 v58, v20
	s_waitcnt lgkmcnt(1)
; #define LAS __attribute__((address_space(3)))
; DI unsigned pk2(float lo, float hi) { f32x2 v = {lo, hi}; bf16v2 b = __builtin_convertvector(v, bf16v2); return __builtin_bit_cast(unsigned, b); }
; #define MFMA32(a, b, c) __builtin_amdgcn_mfma_f32_16x16x32_bf16((a), (b), (c), 0, 0, 0)
; DI void na_phase(LAS unsigned char* lds, const Args& A, const bf16* proj, bf16* nao, int T, int nB, unsigned* counter, int tid_in) {
;     ...
;             f32x4 O[4];
; #pragma unroll
;             for (int mt = 0; mt < 4; ++mt) O[mt] = (f32x4){0.f, 0.f, 0.f, 0.f};
; #pragma unroll
;             for (int rr = 0; rr < 4; ++rr) { const int sl = (rs + 4 * kh + rr) & 7;
;                 const u32x4 pw = (u32x4){pk2(sT[rr][0][0], sT[rr][0][1]), pk2(sT[rr][0][2], sT[rr][0][3]), pk2(sT[rr][1][0], sT[rr][1][1]), pk2(sT[rr][1][2], sT[rr][1][3])};
;                 const bf16x8 pb = __builtin_bit_cast(bf16x8, pw);
; #pragma unroll
;                 for (int mt = 0; mt < 4; ++mt) { const int dd = 16 * mt + l15, sw = 2 * ((dd >> 1) & 7);
;                     const LAS unsigned char* vb = lds + NA_V + sl * 8192 + dd * 128;
;                     const u32x2 lo = *(const LAS u32x2*)(vb + ((((cs0 >> 2) + g) ^ sw) * 8)), hi = *(const LAS u32x2*)(vb + ((((cs0 >> 2) + 4 + g) ^ sw) * 8));
;                     const u32x4 vv = (u32x4){lo.x, lo.y, hi.x, hi.y};
;                     O[mt] = MFMA32(__builtin_bit_cast(bf16x8, vv), pb, O[mt]); } }
;             LAS float* MG = (LAS float*)(lds + NA_MRG + qg * 4608) + lane;
;             if (kh == 1) { MG[0] = mx; MG[64] = lsum;
; #pragma unroll
;                 for (int mt = 0; mt < 4; ++mt)
; #pragma unroll
;                     for (int e = 0; e < 4; ++e) MG[(2 + mt * 4 + e) * 64] = O[mt][e]; }
	v_mov_b32_e32 v60, v24
	v_mov_b32_e32 v61, v25
	v_mov_b32_e32 v24, v22
	v_mov_b32_e32 v25, v23
	v_mov_b32_e32 v59, v21
	s_waitcnt lgkmcnt(0)
	v_add_f32_e32 v54, v39, v54
	v_mfma_f32_16x16x32_bf16 v[20:23], v[24:27], v[16:19], 0
	ds_read2st64_b64 v[24:27], v28 offset0:8 offset1:12
	ds_read2st64_b64 v[62:65], v55 offset0:8 offset1:12
	v_add_u32_e32 v28, v74, v29
	v_add_u32_e32 v29, v28, v75
	v_add_u32_e32 v28, v28, v76
	s_waitcnt lgkmcnt(1)
	v_mov_b32_e32 v104, v24
	v_mov_b32_e32 v105, v25
	s_waitcnt lgkmcnt(0)
	v_mov_b32_e32 v106, v62
	v_mov_b32_e32 v107, v63
	v_mov_b32_e32 v62, v26
	v_mov_b32_e32 v63, v27
	v_mfma_f32_16x16x32_bf16 v[58:61], v[58:61], v[16:19], 0
	ds_read2st64_b64 v[108:111], v28 offset1:4
	v_cvt_pk_bf16_f32 v24, v116, v117
	v_cvt_pk_bf16_f32 v25, v118, v119
	v_mfma_f32_16x16x32_bf16 v[104:107], v[104:107], v[16:19], 0
	v_cvt_pk_bf16_f32 v26, v67, v66
	s_waitcnt lgkmcnt(0)
	v_mov_b32_e32 v114, v108
	v_mov_b32_e32 v115, v109
	v_mfma_f32_16x16x32_bf16 v[16:19], v[62:65], v[16:19], 0
	ds_read2st64_b64 v[62:65], v29 offset1:4
	v_cvt_pk_bf16_f32 v27, v120, v121
	s_waitcnt lgkmcnt(0)
	v_mov_b32_e32 v108, v64
	v_mov_b32_e32 v109, v65
	v_mov_b32_e32 v112, v62
	v_mov_b32_e32 v113, v63
	v_mfma_f32_16x16x32_bf16 v[20:23], v[108:111], v[24:27], v[20:23]
	ds_read2st64_b64 v[62:65], v29 offset0:8 offset1:12
	ds_read2st64_b64 v[108:111], v28 offset0:8 offset1:12
	v_add_u32_e32 v28, v74, v30
	v_add_u32_e32 v29, v28, v75
	v_mfma_f32_16x16x32_bf16 v[58:61], v[112:115], v[24:27], v[58:61]
	v_add_u32_e32 v28, v28, v76
	s_waitcnt lgkmcnt(0)
	v_mov_b32_e32 v114, v108
	v_mov_b32_e32 v115, v109
	v_mov_b32_e32 v108, v64
	v_mov_b32_e32 v109, v65
	v_mov_b32_e32 v112, v62
	v_mov_b32_e32 v113, v63
	v_mfma_f32_16x16x32_bf16 v[16:19], v[108:111], v[24:27], v[16:19]
	ds_read2st64_b64 v[62:65], v29 offset1:4
	ds_read2st64_b64 v[108:111], v28 offset1:4
	v_mfma_f32_16x16x32_bf16 v[104:107], v[112:115], v[24:27], v[104:107]
	v_cvt_pk_bf16_f32 v24, v122, v123
	v_cvt_pk_bf16_f32 v25, v124, v125
	s_waitcnt lgkmcnt(0)
	v_mov_b32_e32 v114, v108
	v_mov_b32_e32 v115, v109
	v_mov_b32_e32 v108, v64
	v_mov_b32_e32 v109, v65
	v_cvt_pk_bf16_f32 v26, v126, v127
	v_cvt_pk_bf16_f32 v27, v128, v129
	v_mov_b32_e32 v112, v62
	v_mov_b32_e32 v113, v63
	v_mfma_f32_16x16x32_bf16 v[20:23], v[108:111], v[24:27], v[20:23]
	ds_read2st64_b64 v[62:65], v29 offset0:8 offset1:12
	ds_read2st64_b64 v[108:111], v28 offset0:8 offset1:12
	v_add_u32_e32 v28, v74, v31
	v_add_u32_e32 v55, v28, v75
	v_mfma_f32_16x16x32_bf16 v[58:61], v[112:115], v[24:27], v[58:61]
	s_waitcnt lgkmcnt(1)
	v_mov_b32_e32 v112, v62
	v_mov_b32_e32 v113, v63
	s_waitcnt lgkmcnt(0)
	v_mov_b32_e32 v114, v108
	v_mov_b32_e32 v115, v109
	v_mov_b32_e32 v108, v64
	v_mov_b32_e32 v109, v65
	v_add_u32_e32 v56, v28, v76
	v_mfma_f32_16x16x32_bf16 v[104:107], v[112:115], v[24:27], v[104:107]
	v_cvt_pk_bf16_f32 v62, v130, v131
	v_cvt_pk_bf16_f32 v63, v132, v133
	v_cvt_pk_bf16_f32 v64, v134, v135
	v_mfma_f32_16x16x32_bf16 v[16:19], v[108:111], v[24:27], v[16:19]
	ds_read2st64_b64 v[24:27], v55 offset1:4
	ds_read2st64_b64 v[108:111], v56 offset1:4
	v_cvt_pk_bf16_f32 v65, v136, v137
	s_waitcnt lgkmcnt(1)
	v_mov_b32_e32 v28, v24
	v_mov_b32_e32 v29, v25
	s_waitcnt lgkmcnt(0)
	v_mov_b32_e32 v30, v108
	v_mov_b32_e32 v31, v109
	v_mov_b32_e32 v108, v26
	v_mov_b32_e32 v109, v27
	v_mfma_f32_16x16x32_bf16 v[28:31], v[28:31], v[62:65], v[58:61]
	s_nop 0
	v_mfma_f32_16x16x32_bf16 v[24:27], v[108:111], v[62:65], v[20:23]
	s_nop 0
	ds_read2st64_b64 v[58:61], v55 offset0:8 offset1:12
	ds_read2st64_b64 v[108:111], v56 offset0:8 offset1:12
	s_waitcnt lgkmcnt(1)
	v_mov_b32_e32 v20, v58
	v_mov_b32_e32 v21, v59
	s_waitcnt lgkmcnt(0)
	v_mov_b32_e32 v22, v108
	v_mov_b32_e32 v23, v109
	v_mov_b32_e32 v108, v60
	v_mov_b32_e32 v109, v61
	v_mfma_f32_16x16x32_bf16 v[20:23], v[20:23], v[62:65], v[104:107]
	s_nop 0
	v_mfma_f32_16x16x32_bf16 v[16:19], v[108:111], v[62:65], v[16:19]
	s_and_saveexec_b64 s[0:1], s[42:43]
	s_cbranch_execz .LBB0_403
	ds_write2st64_b32 v103, v38, v54 offset1:1
	ds_write2st64_b32 v103, v28, v29 offset0:2 offset1:3
	ds_write2st64_b32 v103, v30, v31 offset0:4 offset1:5
	ds_write2st64_b32 v103, v24, v25 offset0:6 offset1:7
	ds_write2st64_b32 v103, v26, v27 offset0:8 offset1:9
	ds_write2st64_b32 v103, v20, v21 offset0:10 offset1:11
	ds_write2st64_b32 v103, v22, v23 offset0:12 offset1:13
	ds_write2st64_b32 v103, v16, v17 offset0:14 offset1:15
	ds_write2st64_b32 v103, v18, v19 offset0:16 offset1:17
